# work-queue scalar atomic issued by wave 0 before the head barrier of the queue iteration, consumed after it
# baseline (speedup 1.0000x reference)
.LBB0_315:
	v_mov_b32_e32 v0, v172
	v_readfirstlane_b32 s99, v172
	s_nop 1
	s_cmp_lg_u32 s99, 0
	s_cbranch_scc1 .Lqe_skip_1
	s_add_u32 s99, s8, 4
	v_readfirstlane_b32 s98, v253
	s_nop 1
	s_cmp_lg_u32 s98, s99
	s_cbranch_scc1 .Lqe_skip_1
	s_mov_b32 s98, 1
	s_atomic_add s98, s[8:9], 0x4 glc
.Lqe_skip_1:
	s_barrier
	s_nop 0
	v_cmp_eq_u32_e32 vcc, 0, v0
	s_and_saveexec_b64 s[0:1], vcc
	s_cbranch_execz .LBB0_319
	s_add_u32 s99, s8, 4
	v_cmp_eq_u32_e32 vcc, s99, v253
	s_nop 4
	s_cbranch_vccnz .Lqf_dyn_1
	v_mov_b32_e32 v253, s99
	v_mov_b32_e32 v0, v254
	s_branch .Lqf_wr_1
.Lqf_dyn_1:
	s_waitcnt lgkmcnt(0)
	v_add_u32_e32 v0, s98, v255

.LBB0_462:
	v_mov_b32_e32 v0, v172
	v_readfirstlane_b32 s99, v172
	s_nop 1
	s_cmp_lg_u32 s99, 0
	s_cbranch_scc1 .Lqe_skip_2
	s_add_u32 s99, s6, 8
	v_readfirstlane_b32 s98, v253
	s_nop 1
	s_cmp_lg_u32 s98, s99
	s_cbranch_scc1 .Lqe_skip_2
	s_mov_b32 s98, 1
	s_atomic_add s98, s[6:7], 0x8 glc
.Lqe_skip_2:
	s_barrier
	s_nop 0
	v_cmp_eq_u32_e32 vcc, 0, v0
	s_and_saveexec_b64 s[0:1], vcc
	s_cbranch_execz .LBB0_466
	s_add_u32 s99, s6, 8
	v_cmp_eq_u32_e32 vcc, s99, v253
	s_nop 4
	s_cbranch_vccnz .Lqf_dyn_2
	v_mov_b32_e32 v253, s99
	v_mov_b32_e32 v0, v254
	s_branch .Lqf_wr_2

.LBB0_578:
	v_readfirstlane_b32 s99, v172
	s_nop 1
	s_cmp_lg_u32 s99, 0
	s_cbranch_scc1 .Lqe_skip_3
	s_add_u32 s99, s20, 0
	v_readfirstlane_b32 s98, v253
	s_nop 1
	s_cmp_lg_u32 s98, s99
	s_cbranch_scc1 .Lqe_skip_3
	s_mov_b32 s98, 1
	s_atomic_add s98, s[20:21], 0x0 glc
.Lqe_skip_3:
	s_barrier
	s_and_saveexec_b64 s[0:1], s[36:37]
	s_cbranch_execz .LBB0_582
	s_add_u32 s99, s20, 0
	v_cmp_eq_u32_e32 vcc, s99, v253
	s_nop 4
	s_cbranch_vccnz .Lqf_dyn_3
	v_mov_b32_e32 v253, s99
	v_mov_b32_e32 v0, v254
	s_branch .Lqf_wr_3

.LBB0_805:
	v_mov_b32_e32 v0, v172
	s_waitcnt lgkmcnt(0)
	v_readfirstlane_b32 s99, v172
	s_nop 1
	s_cmp_lg_u32 s99, 0
	s_cbranch_scc1 .Lqe_skip_4
	s_add_u32 s99, s26, 12
	v_readfirstlane_b32 s98, v253
	s_nop 1
	s_cmp_lg_u32 s98, s99
	s_cbranch_scc1 .Lqe_skip_4
	s_mov_b32 s98, 1
	s_atomic_add s98, s[26:27], 0xc glc
.Lqe_skip_4:
	s_barrier
	s_nop 0
	v_cmp_eq_u32_e32 vcc, 0, v0
	s_and_saveexec_b64 s[0:1], vcc
	s_cbranch_execz .LBB0_809
	s_add_u32 s99, s26, 12
	v_cmp_eq_u32_e32 vcc, s99, v253
	s_nop 4
	s_cbranch_vccnz .Lqf_dyn_4
	v_mov_b32_e32 v253, s99
	v_add_u32_e32 v0, -16, v254
	s_branch .Lqf_wr_4
.Lqf_dyn_4:
	s_waitcnt lgkmcnt(0)
	v_add_u32_e32 v0, s98, v255
	v_add_u32_e32 v0, -16, v0
